# sgu unit rewritten by hand (loads requested early, one barrier per head group); scan stage 1 rewritten (f16-operand FMAs, DPP reduction)
# speedup vs baseline: 1.0415x; 1.0244x over previous
.LBB0_74:
	v_mov_b32_e32 v3, v197
	s_mov_b32 s40, 0x3d372713
	s_mov_b32 s41, 0xc0135761
	s_mov_b32 s43, 0x3b000000
	s_add_u32 s36, s12, 0x1ce98100
	s_addc_u32 s37, s13, 0
	s_add_u32 s38, s12, 0x3918100
	s_addc_u32 s39, s13, 0
	v_lshrrev_b32_e32 v1, 6, v3
	s_nop 0
	v_readfirstlane_b32 s42, v1
	v_lshlrev_b32_e32 v70, 2, v3
	global_load_dword v71, v70, s[20:21]
	global_load_dword v72, v70, s[22:23]
	s_lshl_b32 s0, s42, 4
	s_add_i32 s0, s0, s7
	s_mul_i32 s0, s0, 0x2800
	s_add_u32 s60, s14, s0
	s_addc_u32 s61, s15, 0
	s_add_u32 s60, s60, 0xc00
	s_addc_u32 s61, s61, 0
	v_lshlrev_b32_e32 v1, 4, v235
	s_barrier
	global_load_dwordx4 v[4:7], v1, s[60:61]
	v_add_u32_e32 v1, 0x2800, v1
	global_load_dwordx4 v[8:11], v1, s[60:61]
	v_add_u32_e32 v1, 0x2800, v1
	global_load_dwordx4 v[12:15], v1, s[60:61]
	v_add_u32_e32 v1, 0x2800, v1
	global_load_dwordx4 v[16:19], v1, s[60:61]
	v_add_u32_e32 v1, 0x2800, v1
	global_load_dwordx4 v[20:23], v1, s[60:61]
	v_add_u32_e32 v1, 0x2800, v1
	global_load_dwordx4 v[24:27], v1, s[60:61]
	v_add_u32_e32 v1, 0x2800, v1
	global_load_dwordx4 v[28:31], v1, s[60:61]
	v_add_u32_e32 v1, 0x2800, v1
	global_load_dwordx4 v[32:35], v1, s[60:61]
	v_add_u32_e32 v1, 0x2800, v1
	global_load_dwordx4 v[44:47], v1, s[60:61]
	v_add_u32_e32 v1, 0x2800, v1
	global_load_dwordx4 v[48:51], v1, s[60:61]
	v_add_u32_e32 v1, 0x2800, v1
	global_load_dwordx4 v[52:55], v1, s[60:61]
	v_add_u32_e32 v1, 0x2800, v1
	global_load_dwordx4 v[56:59], v1, s[60:61]
	v_add_u32_e32 v1, 0x2800, v1
	global_load_dwordx4 v[88:91], v1, s[60:61]
	v_add_u32_e32 v1, 0x2800, v1
	global_load_dwordx4 v[92:95], v1, s[60:61]
	v_add_u32_e32 v1, 0x2800, v1
	global_load_dwordx4 v[96:99], v1, s[60:61]
	v_add_u32_e32 v1, 0x2800, v1
	global_load_dwordx4 v[100:103], v1, s[60:61]
	v_add_u32_e32 v1, 0x2800, v1
	v_and_b32_e32 v73, 0x7f, v3
	v_add_u32_e32 v74, s7, v73
	v_mul_u32_u24_e32 v74, 0x2800, v74
	v_lshrrev_b32_e32 v75, 7, v3
	v_lshl_add_u32 v74, v75, 5, v74
	v_add_u32_e32 v60, 0xc00, v74
	v_and_b32_e32 v76, 15, v235
	v_lshrrev_b32_e32 v77, 4, v235
	s_lshl_b32 s0, s42, 4
	v_add_u32_e32 v78, s0, v76
	v_add_u32_e32 v79, s7, v78
	v_mul_u32_u24_e32 v80, 0x2800, v79
	v_lshl_add_u32 v80, v77, 3, v80
	v_add_u32_e32 v61, 0x800, v80
	v_lshlrev_b32_e32 v81, 10, v79
	v_lshl_add_u32 v62, v77, 3, v81
	v_lshlrev_b32_e32 v63, 2, v78
	v_lshlrev_b32_e32 v82, 8, v78
	v_lshl_add_u32 v64, v77, 4, v82
	v_lshlrev_b32_e32 v83, 1, v73
	v_lshlrev_b32_e32 v84, 4, v75
	v_mul_u32_u24_e32 v85, 0x110, v84
	v_add_u32_e32 v65, v83, v85
	v_add_u32_e32 v65, 5120, v65
	v_mul_u32_u24_e32 v86, 0x110, v76
	v_lshl_add_u32 v86, v77, 4, v86
	v_add_u32_e32 v66, 5120, v86
	v_lshlrev_b32_e32 v67, 2, v84
	v_lshlrev_b32_e32 v87, 2, v73
	global_load_dwordx4 v[104:107], v60, s[14:15]
	global_load_dwordx4 v[108:111], v60, s[14:15] offset:16
	global_load_dwordx2 v[112:113], v61, s[14:15] offset:0
	global_load_dwordx2 v[114:115], v61, s[14:15] offset:32
	global_load_dwordx2 v[116:117], v61, s[14:15] offset:64
	global_load_dwordx2 v[118:119], v61, s[14:15] offset:96
	global_load_dword v121, v63, s[16:17]
	global_load_dwordx4 v[122:125], v64, s[38:39] offset:0
	global_load_dwordx4 v[126:129], v64, s[38:39] offset:64
	global_load_dwordx4 v[130:133], v64, s[38:39] offset:128
	global_load_dwordx4 v[134:137], v64, s[38:39] offset:192
	s_waitcnt vmcnt(27)
	ds_write_b32 v70, v71 offset:1024
	ds_write_b32 v70, v72 offset:3072
	v_lshrrev_b32_e32 v84, 5, v235
	s_lshl_b32 s0, s42, 6
	v_lshl_add_u32 v84, v84, 3, s0
	v_mov_b32_e32 v85, 0x3727c5ac
	s_mov_b32 s45, 0
	s_waitcnt vmcnt(23)
	s_branch .Lsgu_stats_go
.Lsgu_stats:
	s_cmp_eq_u32 s45, 1
	s_cbranch_scc1 .Lsgu_st1
	s_cmp_eq_u32 s45, 2
	s_cbranch_scc1 .Lsgu_st2
	s_waitcnt vmcnt(11)
	v_mov_b32_e32 v4, v88
	v_mov_b32_e32 v5, v89
	v_mov_b32_e32 v6, v90
	v_mov_b32_e32 v7, v91
	v_mov_b32_e32 v8, v92
	v_mov_b32_e32 v9, v93
	v_mov_b32_e32 v10, v94
	v_mov_b32_e32 v11, v95
	v_mov_b32_e32 v12, v96
	v_mov_b32_e32 v13, v97
	v_mov_b32_e32 v14, v98
	v_mov_b32_e32 v15, v99
	v_mov_b32_e32 v16, v100
	v_mov_b32_e32 v17, v101
	v_mov_b32_e32 v18, v102
	v_mov_b32_e32 v19, v103
	s_branch .Lsgu_stats_go
.Lsgu_st1:
	s_waitcnt vmcnt(19)
	v_mov_b32_e32 v4, v20
	v_mov_b32_e32 v5, v21
	v_mov_b32_e32 v6, v22
	v_mov_b32_e32 v7, v23
	v_mov_b32_e32 v8, v24
	v_mov_b32_e32 v9, v25
	v_mov_b32_e32 v10, v26
	v_mov_b32_e32 v11, v27
	v_mov_b32_e32 v12, v28
	v_mov_b32_e32 v13, v29
	v_mov_b32_e32 v14, v30
	v_mov_b32_e32 v15, v31
	v_mov_b32_e32 v16, v32
	v_mov_b32_e32 v17, v33
	v_mov_b32_e32 v18, v34
	v_mov_b32_e32 v19, v35
	s_branch .Lsgu_stats_go
.Lsgu_st2:
	s_waitcnt vmcnt(15)
	v_mov_b32_e32 v4, v44
	v_mov_b32_e32 v5, v45
	v_mov_b32_e32 v6, v46
	v_mov_b32_e32 v7, v47
	v_mov_b32_e32 v8, v48
	v_mov_b32_e32 v9, v49
	v_mov_b32_e32 v10, v50
	v_mov_b32_e32 v11, v51
	v_mov_b32_e32 v12, v52
	v_mov_b32_e32 v13, v53
	v_mov_b32_e32 v14, v54
	v_mov_b32_e32 v15, v55
	v_mov_b32_e32 v16, v56
	v_mov_b32_e32 v17, v57
	v_mov_b32_e32 v18, v58
	v_mov_b32_e32 v19, v59
.Lsgu_stats_go:
	v_mov_b32_e32 v36, 0
	v_mov_b32_e32 v40, 0
	v_cvt_f32_f16_e32 v70, v4
	v_cvt_f32_f16_sdwa v73, v4 dst_sel:DWORD dst_unused:UNUSED_PAD src0_sel:WORD_1
	v_cvt_f32_f16_e32 v76, v5
	v_cvt_f32_f16_sdwa v79, v5 dst_sel:DWORD dst_unused:UNUSED_PAD src0_sel:WORD_1
	v_mul_f32_e32 v71, v70, v70
	v_mul_f32_e32 v74, v73, v73
	v_mul_f32_e32 v77, v76, v76
	v_mul_f32_e32 v80, v79, v79
	v_mul_f32_e32 v72, s41, v70
	v_mul_f32_e32 v75, s41, v73
	v_mul_f32_e32 v78, s41, v76
	v_mul_f32_e32 v81, s41, v79
	v_fma_f32 v71, v71, s40, 1.0
	v_fma_f32 v74, v74, s40, 1.0
	v_fma_f32 v77, v77, s40, 1.0
	v_fma_f32 v80, v80, s40, 1.0
	v_mul_f32_e32 v71, v71, v72
	v_mul_f32_e32 v74, v74, v75
	v_mul_f32_e32 v77, v77, v78
	v_mul_f32_e32 v80, v80, v81
	v_exp_f32_e32 v71, v71
	v_exp_f32_e32 v74, v74
	v_exp_f32_e32 v77, v77
	v_exp_f32_e32 v80, v80
	v_add_f32_e32 v71, 1.0, v71
	v_add_f32_e32 v74, 1.0, v74
	v_add_f32_e32 v77, 1.0, v77
	v_add_f32_e32 v80, 1.0, v80
	v_rcp_f32_e32 v71, v71
	v_rcp_f32_e32 v74, v74
	v_rcp_f32_e32 v77, v77
	v_rcp_f32_e32 v80, v80
	v_mul_f32_e32 v71, v71, v70
	v_mul_f32_e32 v74, v74, v73
	v_mul_f32_e32 v77, v77, v76
	v_mul_f32_e32 v80, v80, v79
	v_add_f32_e32 v36, v36, v71
	v_fmac_f32_e32 v40, v71, v71
	v_add_f32_e32 v36, v36, v74
	v_fmac_f32_e32 v40, v74, v74
	v_add_f32_e32 v36, v36, v77
	v_fmac_f32_e32 v40, v77, v77
	v_add_f32_e32 v36, v36, v80
	v_fmac_f32_e32 v40, v80, v80
	v_cvt_f32_f16_e32 v70, v6
	v_cvt_f32_f16_sdwa v73, v6 dst_sel:DWORD dst_unused:UNUSED_PAD src0_sel:WORD_1
	v_cvt_f32_f16_e32 v76, v7
	v_cvt_f32_f16_sdwa v79, v7 dst_sel:DWORD dst_unused:UNUSED_PAD src0_sel:WORD_1
	v_mul_f32_e32 v71, v70, v70
	v_mul_f32_e32 v74, v73, v73
	v_mul_f32_e32 v77, v76, v76
	v_mul_f32_e32 v80, v79, v79
	v_mul_f32_e32 v72, s41, v70
	v_mul_f32_e32 v75, s41, v73
	v_mul_f32_e32 v78, s41, v76
	v_mul_f32_e32 v81, s41, v79
	v_fma_f32 v71, v71, s40, 1.0
	v_fma_f32 v74, v74, s40, 1.0
	v_fma_f32 v77, v77, s40, 1.0
	v_fma_f32 v80, v80, s40, 1.0
	v_mul_f32_e32 v71, v71, v72
	v_mul_f32_e32 v74, v74, v75
	v_mul_f32_e32 v77, v77, v78
	v_mul_f32_e32 v80, v80, v81
	v_exp_f32_e32 v71, v71
	v_exp_f32_e32 v74, v74
	v_exp_f32_e32 v77, v77
	v_exp_f32_e32 v80, v80
	v_add_f32_e32 v71, 1.0, v71
	v_add_f32_e32 v74, 1.0, v74
	v_add_f32_e32 v77, 1.0, v77
	v_add_f32_e32 v80, 1.0, v80
	v_rcp_f32_e32 v71, v71
	v_rcp_f32_e32 v74, v74
	v_rcp_f32_e32 v77, v77
	v_rcp_f32_e32 v80, v80
	v_mul_f32_e32 v71, v71, v70
	v_mul_f32_e32 v74, v74, v73
	v_mul_f32_e32 v77, v77, v76
	v_mul_f32_e32 v80, v80, v79
	v_add_f32_e32 v36, v36, v71
	v_fmac_f32_e32 v40, v71, v71
	v_add_f32_e32 v36, v36, v74
	v_fmac_f32_e32 v40, v74, v74
	v_add_f32_e32 v36, v36, v77
	v_fmac_f32_e32 v40, v77, v77
	v_add_f32_e32 v36, v36, v80
	v_fmac_f32_e32 v40, v80, v80
	v_mov_b32_e32 v37, 0
	v_mov_b32_e32 v41, 0
	v_cvt_f32_f16_e32 v70, v8
	v_cvt_f32_f16_sdwa v73, v8 dst_sel:DWORD dst_unused:UNUSED_PAD src0_sel:WORD_1
	v_cvt_f32_f16_e32 v76, v9
	v_cvt_f32_f16_sdwa v79, v9 dst_sel:DWORD dst_unused:UNUSED_PAD src0_sel:WORD_1
	v_mul_f32_e32 v71, v70, v70
	v_mul_f32_e32 v74, v73, v73
	v_mul_f32_e32 v77, v76, v76
	v_mul_f32_e32 v80, v79, v79
	v_mul_f32_e32 v72, s41, v70
	v_mul_f32_e32 v75, s41, v73
	v_mul_f32_e32 v78, s41, v76
	v_mul_f32_e32 v81, s41, v79
	v_fma_f32 v71, v71, s40, 1.0
	v_fma_f32 v74, v74, s40, 1.0
	v_fma_f32 v77, v77, s40, 1.0
	v_fma_f32 v80, v80, s40, 1.0
	v_mul_f32_e32 v71, v71, v72
	v_mul_f32_e32 v74, v74, v75
	v_mul_f32_e32 v77, v77, v78
	v_mul_f32_e32 v80, v80, v81
	v_exp_f32_e32 v71, v71
	v_exp_f32_e32 v74, v74
	v_exp_f32_e32 v77, v77
	v_exp_f32_e32 v80, v80
	v_add_f32_e32 v71, 1.0, v71
	v_add_f32_e32 v74, 1.0, v74
	v_add_f32_e32 v77, 1.0, v77
	v_add_f32_e32 v80, 1.0, v80
	v_rcp_f32_e32 v71, v71
	v_rcp_f32_e32 v74, v74
	v_rcp_f32_e32 v77, v77
	v_rcp_f32_e32 v80, v80
	v_mul_f32_e32 v71, v71, v70
	v_mul_f32_e32 v74, v74, v73
	v_mul_f32_e32 v77, v77, v76
	v_mul_f32_e32 v80, v80, v79
	v_add_f32_e32 v37, v37, v71
	v_fmac_f32_e32 v41, v71, v71
	v_add_f32_e32 v37, v37, v74
	v_fmac_f32_e32 v41, v74, v74
	v_add_f32_e32 v37, v37, v77
	v_fmac_f32_e32 v41, v77, v77
	v_add_f32_e32 v37, v37, v80
	v_fmac_f32_e32 v41, v80, v80
	v_cvt_f32_f16_e32 v70, v10
	v_cvt_f32_f16_sdwa v73, v10 dst_sel:DWORD dst_unused:UNUSED_PAD src0_sel:WORD_1
	v_cvt_f32_f16_e32 v76, v11
	v_cvt_f32_f16_sdwa v79, v11 dst_sel:DWORD dst_unused:UNUSED_PAD src0_sel:WORD_1
	v_mul_f32_e32 v71, v70, v70
	v_mul_f32_e32 v74, v73, v73
	v_mul_f32_e32 v77, v76, v76
	v_mul_f32_e32 v80, v79, v79
	v_mul_f32_e32 v72, s41, v70
	v_mul_f32_e32 v75, s41, v73
	v_mul_f32_e32 v78, s41, v76
	v_mul_f32_e32 v81, s41, v79
	v_fma_f32 v71, v71, s40, 1.0
	v_fma_f32 v74, v74, s40, 1.0
	v_fma_f32 v77, v77, s40, 1.0
	v_fma_f32 v80, v80, s40, 1.0
	v_mul_f32_e32 v71, v71, v72
	v_mul_f32_e32 v74, v74, v75
	v_mul_f32_e32 v77, v77, v78
	v_mul_f32_e32 v80, v80, v81
	v_exp_f32_e32 v71, v71
	v_exp_f32_e32 v74, v74
	v_exp_f32_e32 v77, v77
	v_exp_f32_e32 v80, v80
	v_add_f32_e32 v71, 1.0, v71
	v_add_f32_e32 v74, 1.0, v74
	v_add_f32_e32 v77, 1.0, v77
	v_add_f32_e32 v80, 1.0, v80
	v_rcp_f32_e32 v71, v71
	v_rcp_f32_e32 v74, v74
	v_rcp_f32_e32 v77, v77
	v_rcp_f32_e32 v80, v80
	v_mul_f32_e32 v71, v71, v70
	v_mul_f32_e32 v74, v74, v73
	v_mul_f32_e32 v77, v77, v76
	v_mul_f32_e32 v80, v80, v79
	v_add_f32_e32 v37, v37, v71
	v_fmac_f32_e32 v41, v71, v71
	v_add_f32_e32 v37, v37, v74
	v_fmac_f32_e32 v41, v74, v74
	v_add_f32_e32 v37, v37, v77
	v_fmac_f32_e32 v41, v77, v77
	v_add_f32_e32 v37, v37, v80
	v_fmac_f32_e32 v41, v80, v80
	v_mov_b32_e32 v38, 0
	v_mov_b32_e32 v42, 0
	v_cvt_f32_f16_e32 v70, v12
	v_cvt_f32_f16_sdwa v73, v12 dst_sel:DWORD dst_unused:UNUSED_PAD src0_sel:WORD_1
	v_cvt_f32_f16_e32 v76, v13
	v_cvt_f32_f16_sdwa v79, v13 dst_sel:DWORD dst_unused:UNUSED_PAD src0_sel:WORD_1
	v_mul_f32_e32 v71, v70, v70
	v_mul_f32_e32 v74, v73, v73
	v_mul_f32_e32 v77, v76, v76
	v_mul_f32_e32 v80, v79, v79
	v_mul_f32_e32 v72, s41, v70
	v_mul_f32_e32 v75, s41, v73
	v_mul_f32_e32 v78, s41, v76
	v_mul_f32_e32 v81, s41, v79
	v_fma_f32 v71, v71, s40, 1.0
	v_fma_f32 v74, v74, s40, 1.0
	v_fma_f32 v77, v77, s40, 1.0
	v_fma_f32 v80, v80, s40, 1.0
	v_mul_f32_e32 v71, v71, v72
	v_mul_f32_e32 v74, v74, v75
	v_mul_f32_e32 v77, v77, v78
	v_mul_f32_e32 v80, v80, v81
	v_exp_f32_e32 v71, v71
	v_exp_f32_e32 v74, v74
	v_exp_f32_e32 v77, v77
	v_exp_f32_e32 v80, v80
	v_add_f32_e32 v71, 1.0, v71
	v_add_f32_e32 v74, 1.0, v74
	v_add_f32_e32 v77, 1.0, v77
	v_add_f32_e32 v80, 1.0, v80
	v_rcp_f32_e32 v71, v71
	v_rcp_f32_e32 v74, v74
	v_rcp_f32_e32 v77, v77
	v_rcp_f32_e32 v80, v80
	v_mul_f32_e32 v71, v71, v70
	v_mul_f32_e32 v74, v74, v73
	v_mul_f32_e32 v77, v77, v76
	v_mul_f32_e32 v80, v80, v79
	v_add_f32_e32 v38, v38, v71
	v_fmac_f32_e32 v42, v71, v71
	v_add_f32_e32 v38, v38, v74
	v_fmac_f32_e32 v42, v74, v74
	v_add_f32_e32 v38, v38, v77
	v_fmac_f32_e32 v42, v77, v77
	v_add_f32_e32 v38, v38, v80
	v_fmac_f32_e32 v42, v80, v80
	v_cvt_f32_f16_e32 v70, v14
	v_cvt_f32_f16_sdwa v73, v14 dst_sel:DWORD dst_unused:UNUSED_PAD src0_sel:WORD_1
	v_cvt_f32_f16_e32 v76, v15
	v_cvt_f32_f16_sdwa v79, v15 dst_sel:DWORD dst_unused:UNUSED_PAD src0_sel:WORD_1
	v_mul_f32_e32 v71, v70, v70
	v_mul_f32_e32 v74, v73, v73
	v_mul_f32_e32 v77, v76, v76
	v_mul_f32_e32 v80, v79, v79
	v_mul_f32_e32 v72, s41, v70
	v_mul_f32_e32 v75, s41, v73
	v_mul_f32_e32 v78, s41, v76
	v_mul_f32_e32 v81, s41, v79
	v_fma_f32 v71, v71, s40, 1.0
	v_fma_f32 v74, v74, s40, 1.0
	v_fma_f32 v77, v77, s40, 1.0
	v_fma_f32 v80, v80, s40, 1.0
	v_mul_f32_e32 v71, v71, v72
	v_mul_f32_e32 v74, v74, v75
	v_mul_f32_e32 v77, v77, v78
	v_mul_f32_e32 v80, v80, v81
	v_exp_f32_e32 v71, v71
	v_exp_f32_e32 v74, v74
	v_exp_f32_e32 v77, v77
	v_exp_f32_e32 v80, v80
	v_add_f32_e32 v71, 1.0, v71
	v_add_f32_e32 v74, 1.0, v74
	v_add_f32_e32 v77, 1.0, v77
	v_add_f32_e32 v80, 1.0, v80
	v_rcp_f32_e32 v71, v71
	v_rcp_f32_e32 v74, v74
	v_rcp_f32_e32 v77, v77
	v_rcp_f32_e32 v80, v80
	v_mul_f32_e32 v71, v71, v70
	v_mul_f32_e32 v74, v74, v73
	v_mul_f32_e32 v77, v77, v76
	v_mul_f32_e32 v80, v80, v79
	v_add_f32_e32 v38, v38, v71
	v_fmac_f32_e32 v42, v71, v71
	v_add_f32_e32 v38, v38, v74
	v_fmac_f32_e32 v42, v74, v74
	v_add_f32_e32 v38, v38, v77
	v_fmac_f32_e32 v42, v77, v77
	v_add_f32_e32 v38, v38, v80
	v_fmac_f32_e32 v42, v80, v80
	v_mov_b32_e32 v39, 0
	v_mov_b32_e32 v43, 0
	v_cvt_f32_f16_e32 v70, v16
	v_cvt_f32_f16_sdwa v73, v16 dst_sel:DWORD dst_unused:UNUSED_PAD src0_sel:WORD_1
	v_cvt_f32_f16_e32 v76, v17
	v_cvt_f32_f16_sdwa v79, v17 dst_sel:DWORD dst_unused:UNUSED_PAD src0_sel:WORD_1
	v_mul_f32_e32 v71, v70, v70
	v_mul_f32_e32 v74, v73, v73
	v_mul_f32_e32 v77, v76, v76
	v_mul_f32_e32 v80, v79, v79
	v_mul_f32_e32 v72, s41, v70
	v_mul_f32_e32 v75, s41, v73
	v_mul_f32_e32 v78, s41, v76
	v_mul_f32_e32 v81, s41, v79
	v_fma_f32 v71, v71, s40, 1.0
	v_fma_f32 v74, v74, s40, 1.0
	v_fma_f32 v77, v77, s40, 1.0
	v_fma_f32 v80, v80, s40, 1.0
	v_mul_f32_e32 v71, v71, v72
	v_mul_f32_e32 v74, v74, v75
	v_mul_f32_e32 v77, v77, v78
	v_mul_f32_e32 v80, v80, v81
	v_exp_f32_e32 v71, v71
	v_exp_f32_e32 v74, v74
	v_exp_f32_e32 v77, v77
	v_exp_f32_e32 v80, v80
	v_add_f32_e32 v71, 1.0, v71
	v_add_f32_e32 v74, 1.0, v74
	v_add_f32_e32 v77, 1.0, v77
	v_add_f32_e32 v80, 1.0, v80
	v_rcp_f32_e32 v71, v71
	v_rcp_f32_e32 v74, v74
	v_rcp_f32_e32 v77, v77
	v_rcp_f32_e32 v80, v80
	v_mul_f32_e32 v71, v71, v70
	v_mul_f32_e32 v74, v74, v73
	v_mul_f32_e32 v77, v77, v76
	v_mul_f32_e32 v80, v80, v79
	v_add_f32_e32 v39, v39, v71
	v_fmac_f32_e32 v43, v71, v71
	v_add_f32_e32 v39, v39, v74
	v_fmac_f32_e32 v43, v74, v74
	v_add_f32_e32 v39, v39, v77
	v_fmac_f32_e32 v43, v77, v77
	v_add_f32_e32 v39, v39, v80
	v_fmac_f32_e32 v43, v80, v80
	v_cvt_f32_f16_e32 v70, v18
	v_cvt_f32_f16_sdwa v73, v18 dst_sel:DWORD dst_unused:UNUSED_PAD src0_sel:WORD_1
	v_cvt_f32_f16_e32 v76, v19
	v_cvt_f32_f16_sdwa v79, v19 dst_sel:DWORD dst_unused:UNUSED_PAD src0_sel:WORD_1
	v_mul_f32_e32 v71, v70, v70
	v_mul_f32_e32 v74, v73, v73
	v_mul_f32_e32 v77, v76, v76
	v_mul_f32_e32 v80, v79, v79
	v_mul_f32_e32 v72, s41, v70
	v_mul_f32_e32 v75, s41, v73
	v_mul_f32_e32 v78, s41, v76
	v_mul_f32_e32 v81, s41, v79
	v_fma_f32 v71, v71, s40, 1.0
	v_fma_f32 v74, v74, s40, 1.0
	v_fma_f32 v77, v77, s40, 1.0
	v_fma_f32 v80, v80, s40, 1.0
	v_mul_f32_e32 v71, v71, v72
	v_mul_f32_e32 v74, v74, v75
	v_mul_f32_e32 v77, v77, v78
	v_mul_f32_e32 v80, v80, v81
	v_exp_f32_e32 v71, v71
	v_exp_f32_e32 v74, v74
	v_exp_f32_e32 v77, v77
	v_exp_f32_e32 v80, v80
	v_add_f32_e32 v71, 1.0, v71
	v_add_f32_e32 v74, 1.0, v74
	v_add_f32_e32 v77, 1.0, v77
	v_add_f32_e32 v80, 1.0, v80
	v_rcp_f32_e32 v71, v71
	v_rcp_f32_e32 v74, v74
	v_rcp_f32_e32 v77, v77
	v_rcp_f32_e32 v80, v80
	v_mul_f32_e32 v71, v71, v70
	v_mul_f32_e32 v74, v74, v73
	v_mul_f32_e32 v77, v77, v76
	v_mul_f32_e32 v80, v80, v79
	v_add_f32_e32 v39, v39, v71
	v_fmac_f32_e32 v43, v71, v71
	v_add_f32_e32 v39, v39, v74
	v_fmac_f32_e32 v43, v74, v74
	v_add_f32_e32 v39, v39, v77
	v_fmac_f32_e32 v43, v77, v77
	v_add_f32_e32 v39, v39, v80
	v_fmac_f32_e32 v43, v80, v80
	s_nop 1
	v_permlane32_swap_b32_e32 v36, v38
	v_permlane32_swap_b32_e32 v37, v39
	v_permlane32_swap_b32_e32 v40, v42
	v_permlane32_swap_b32_e32 v41, v43
	v_add_f32_e32 v36, v36, v38
	v_add_f32_e32 v37, v37, v39
	v_add_f32_e32 v40, v40, v42
	v_add_f32_e32 v41, v41, v43
	ds_swizzle_b32 v70, v36 offset:0x401f
	ds_swizzle_b32 v71, v37 offset:0x401f
	ds_swizzle_b32 v72, v40 offset:0x401f
	ds_swizzle_b32 v73, v41 offset:0x401f
	s_waitcnt lgkmcnt(0)
	v_add_f32_e32 v36, v36, v70
	v_add_f32_e32 v37, v37, v71
	v_add_f32_e32 v40, v40, v72
	v_add_f32_e32 v41, v41, v73
	s_nop 1
	v_add_f32_dpp v36, v36, v36 quad_perm:[1,0,3,2] row_mask:0xf bank_mask:0xf
	v_add_f32_dpp v37, v37, v37 quad_perm:[1,0,3,2] row_mask:0xf bank_mask:0xf
	v_add_f32_dpp v40, v40, v40 quad_perm:[1,0,3,2] row_mask:0xf bank_mask:0xf
	v_add_f32_dpp v41, v41, v41 quad_perm:[1,0,3,2] row_mask:0xf bank_mask:0xf
	s_nop 1
	v_add_f32_dpp v36, v36, v36 quad_perm:[2,3,0,1] row_mask:0xf bank_mask:0xf
	v_add_f32_dpp v37, v37, v37 quad_perm:[2,3,0,1] row_mask:0xf bank_mask:0xf
	v_add_f32_dpp v40, v40, v40 quad_perm:[2,3,0,1] row_mask:0xf bank_mask:0xf
	v_add_f32_dpp v41, v41, v41 quad_perm:[2,3,0,1] row_mask:0xf bank_mask:0xf
	s_nop 1
	v_add_f32_dpp v36, v36, v36 row_half_mirror row_mask:0xf bank_mask:0xf
	v_add_f32_dpp v37, v37, v37 row_half_mirror row_mask:0xf bank_mask:0xf
	v_add_f32_dpp v40, v40, v40 row_half_mirror row_mask:0xf bank_mask:0xf
	v_add_f32_dpp v41, v41, v41 row_half_mirror row_mask:0xf bank_mask:0xf
	s_nop 1
	v_add_f32_dpp v36, v36, v36 row_mirror row_mask:0xf bank_mask:0xf
	v_add_f32_dpp v37, v37, v37 row_mirror row_mask:0xf bank_mask:0xf
	v_add_f32_dpp v40, v40, v40 row_mirror row_mask:0xf bank_mask:0xf
	v_add_f32_dpp v41, v41, v41 row_mirror row_mask:0xf bank_mask:0xf
	s_nop 1
	v_mul_f32_e32 v36, s43, v36
	v_mul_f32_e32 v40, s43, v40
	v_mul_f32_e32 v37, s43, v37
	v_mul_f32_e32 v41, s43, v41
	v_fma_f32 v40, -v36, v36, v40
	v_fma_f32 v41, -v37, v37, v41
	v_max_f32_e32 v40, 0, v40
	v_max_f32_e32 v41, 0, v41
	v_add_f32_e32 v40, v40, v85
	v_add_f32_e32 v41, v41, v85
	v_rsq_f32_e32 v40, v40
	v_rsq_f32_e32 v41, v41
	s_lshl_b32 s0, s45, 4
	v_add_u32_e32 v86, s0, v84
	s_mov_b64 s[72:73], exec
	s_mov_b32 s0, 1
	s_mov_b32 s1, 1
	s_mov_b64 exec, s[0:1]
	ds_write_b32 v86, v36 offset:0
	ds_write_b32 v86, v40 offset:512
	ds_write_b32 v86, v37 offset:4
	ds_write_b32 v86, v41 offset:516
	s_mov_b64 exec, s[72:73]
	s_add_i32 s45, s45, 1
	s_cmp_lg_u32 s45, 4
	s_cbranch_scc1 .Lsgu_stats
	s_waitcnt lgkmcnt(0)
	s_barrier
	ds_read_b32 v68, v87 offset:0
	ds_read_b32 v69, v87 offset:512
	s_mov_b32 s44, 0
	s_mov_b64 s[62:63], s[38:39]
	s_mov_b64 s[64:65], s[16:17]
	s_waitcnt vmcnt(0)
.Lsgu_g8:
	v_mov_b32_e32 v20, v104
	v_mov_b32_e32 v21, v105
	v_mov_b32_e32 v22, v106
	v_mov_b32_e32 v23, v107
	v_mov_b32_e32 v24, v108
	v_mov_b32_e32 v25, v109
	v_mov_b32_e32 v26, v110
	v_mov_b32_e32 v27, v111
	v_mov_b32_e32 v28, v112
	v_mov_b32_e32 v29, v113
	v_mov_b32_e32 v30, v114
	v_mov_b32_e32 v31, v115
	v_mov_b32_e32 v32, v116
	v_mov_b32_e32 v33, v117
	v_mov_b32_e32 v34, v118
	v_mov_b32_e32 v35, v119
	v_mov_b32_e32 v36, v121
	v_add_u32_e32 v60, 0x80, v60
	v_add_u32_e32 v61, 0x80, v61
	s_cmp_eq_u32 s44, 0x380
	s_cbranch_scc1 .Lsgu_nopf
	s_add_u32 s64, s64, 0x200
	s_addc_u32 s65, s65, 0
	global_load_dwordx4 v[104:107], v60, s[14:15]
	global_load_dwordx4 v[108:111], v60, s[14:15] offset:16
	global_load_dwordx2 v[112:113], v61, s[14:15] offset:0
	global_load_dwordx2 v[114:115], v61, s[14:15] offset:32
	global_load_dwordx2 v[116:117], v61, s[14:15] offset:64
	global_load_dwordx2 v[118:119], v61, s[14:15] offset:96
	global_load_dword v121, v63, s[64:65]
	s_branch .Lsgu_cont
.Lsgu_nopf:
	s_waitcnt vmcnt(4)
.Lsgu_cont:
	s_lshl_b32 s0, s44, 1
	v_add_u32_e32 v102, s0, v67
	ds_read_b128 v[70:73], v102 offset:1024
	ds_read_b128 v[74:77], v102 offset:1040
	ds_read_b128 v[78:81], v102 offset:1056
	ds_read_b128 v[82:85], v102 offset:1072
	ds_read_b128 v[86:89], v102 offset:3072
	ds_read_b128 v[90:93], v102 offset:3088
	ds_read_b128 v[94:97], v102 offset:3104
	ds_read_b128 v[98:101], v102 offset:3120
	s_waitcnt lgkmcnt(0)
	v_cvt_f32_f16_e32 v56, v20
	v_cvt_f32_f16_sdwa v59, v20 dst_sel:DWORD dst_unused:UNUSED_PAD src0_sel:WORD_1
	v_cvt_f32_f16_e32 v39, v21
	v_cvt_f32_f16_sdwa v10, v21 dst_sel:DWORD dst_unused:UNUSED_PAD src0_sel:WORD_1
	v_mul_f32_e32 v57, v56, v56
	v_mul_f32_e32 v37, v59, v59
	v_mul_f32_e32 v103, v39, v39
	v_mul_f32_e32 v11, v10, v10
	v_mul_f32_e32 v58, s41, v56
	v_mul_f32_e32 v38, s41, v59
	v_mul_f32_e32 v9, s41, v39
	v_mul_f32_e32 v12, s41, v10
	v_fma_f32 v57, v57, s40, 1.0
	v_fma_f32 v37, v37, s40, 1.0
	v_fma_f32 v103, v103, s40, 1.0
	v_fma_f32 v11, v11, s40, 1.0
	v_mul_f32_e32 v57, v57, v58
	v_mul_f32_e32 v37, v37, v38
	v_mul_f32_e32 v103, v103, v9
	v_mul_f32_e32 v11, v11, v12
	v_exp_f32_e32 v57, v57
	v_exp_f32_e32 v37, v37
	v_exp_f32_e32 v103, v103
	v_exp_f32_e32 v11, v11
	v_add_f32_e32 v57, 1.0, v57
	v_add_f32_e32 v37, 1.0, v37
	v_add_f32_e32 v103, 1.0, v103
	v_add_f32_e32 v11, 1.0, v11
	v_rcp_f32_e32 v57, v57
	v_rcp_f32_e32 v37, v37
	v_rcp_f32_e32 v103, v103
	v_rcp_f32_e32 v11, v11
	v_fma_f32 v57, v57, v56, -v68
	v_fma_f32 v37, v37, v59, -v68
	v_fma_f32 v103, v103, v39, -v68
	v_fma_f32 v11, v11, v10, -v68
	v_mul_f32_e32 v57, v69, v57
	v_mul_f32_e32 v37, v69, v37
	v_mul_f32_e32 v103, v69, v103
	v_mul_f32_e32 v11, v69, v11
	v_fma_mixlo_f16 v58, v57, v70, v86
	v_fma_mixlo_f16 v38, v37, v71, v87
	v_fma_mixlo_f16 v9, v103, v72, v88
	v_fma_mixlo_f16 v12, v11, v73, v89
	ds_write_b16 v65, v58 offset:0
	ds_write_b16 v65, v38 offset:272
	ds_write_b16 v65, v9 offset:544
	ds_write_b16 v65, v12 offset:816
	v_cvt_f32_f16_e32 v56, v22
	v_cvt_f32_f16_sdwa v59, v22 dst_sel:DWORD dst_unused:UNUSED_PAD src0_sel:WORD_1
	v_cvt_f32_f16_e32 v39, v23
	v_cvt_f32_f16_sdwa v10, v23 dst_sel:DWORD dst_unused:UNUSED_PAD src0_sel:WORD_1
	v_mul_f32_e32 v57, v56, v56
	v_mul_f32_e32 v37, v59, v59
	v_mul_f32_e32 v103, v39, v39
	v_mul_f32_e32 v11, v10, v10
	v_mul_f32_e32 v58, s41, v56
	v_mul_f32_e32 v38, s41, v59
	v_mul_f32_e32 v9, s41, v39
	v_mul_f32_e32 v12, s41, v10
	v_fma_f32 v57, v57, s40, 1.0
	v_fma_f32 v37, v37, s40, 1.0
	v_fma_f32 v103, v103, s40, 1.0
	v_fma_f32 v11, v11, s40, 1.0
	v_mul_f32_e32 v57, v57, v58
	v_mul_f32_e32 v37, v37, v38
	v_mul_f32_e32 v103, v103, v9
	v_mul_f32_e32 v11, v11, v12
	v_exp_f32_e32 v57, v57
	v_exp_f32_e32 v37, v37
	v_exp_f32_e32 v103, v103
	v_exp_f32_e32 v11, v11
	v_add_f32_e32 v57, 1.0, v57
	v_add_f32_e32 v37, 1.0, v37
	v_add_f32_e32 v103, 1.0, v103
	v_add_f32_e32 v11, 1.0, v11
	v_rcp_f32_e32 v57, v57
	v_rcp_f32_e32 v37, v37
	v_rcp_f32_e32 v103, v103
	v_rcp_f32_e32 v11, v11
	v_fma_f32 v57, v57, v56, -v68
	v_fma_f32 v37, v37, v59, -v68
	v_fma_f32 v103, v103, v39, -v68
	v_fma_f32 v11, v11, v10, -v68
	v_mul_f32_e32 v57, v69, v57
	v_mul_f32_e32 v37, v69, v37
	v_mul_f32_e32 v103, v69, v103
	v_mul_f32_e32 v11, v69, v11
	v_fma_mixlo_f16 v58, v57, v74, v90
	v_fma_mixlo_f16 v38, v37, v75, v91
	v_fma_mixlo_f16 v9, v103, v76, v92
	v_fma_mixlo_f16 v12, v11, v77, v93
	ds_write_b16 v65, v58 offset:1088
	ds_write_b16 v65, v38 offset:1360
	ds_write_b16 v65, v9 offset:1632
	ds_write_b16 v65, v12 offset:1904
	v_cvt_f32_f16_e32 v56, v24
	v_cvt_f32_f16_sdwa v59, v24 dst_sel:DWORD dst_unused:UNUSED_PAD src0_sel:WORD_1
	v_cvt_f32_f16_e32 v39, v25
	v_cvt_f32_f16_sdwa v10, v25 dst_sel:DWORD dst_unused:UNUSED_PAD src0_sel:WORD_1
	v_mul_f32_e32 v57, v56, v56
	v_mul_f32_e32 v37, v59, v59
	v_mul_f32_e32 v103, v39, v39
	v_mul_f32_e32 v11, v10, v10
	v_mul_f32_e32 v58, s41, v56
	v_mul_f32_e32 v38, s41, v59
	v_mul_f32_e32 v9, s41, v39
	v_mul_f32_e32 v12, s41, v10
	v_fma_f32 v57, v57, s40, 1.0
	v_fma_f32 v37, v37, s40, 1.0
	v_fma_f32 v103, v103, s40, 1.0
	v_fma_f32 v11, v11, s40, 1.0
	v_mul_f32_e32 v57, v57, v58
	v_mul_f32_e32 v37, v37, v38
	v_mul_f32_e32 v103, v103, v9
	v_mul_f32_e32 v11, v11, v12
	v_exp_f32_e32 v57, v57
	v_exp_f32_e32 v37, v37
	v_exp_f32_e32 v103, v103
	v_exp_f32_e32 v11, v11
	v_add_f32_e32 v57, 1.0, v57
	v_add_f32_e32 v37, 1.0, v37
	v_add_f32_e32 v103, 1.0, v103
	v_add_f32_e32 v11, 1.0, v11
	v_rcp_f32_e32 v57, v57
	v_rcp_f32_e32 v37, v37
	v_rcp_f32_e32 v103, v103
	v_rcp_f32_e32 v11, v11
	v_fma_f32 v57, v57, v56, -v68
	v_fma_f32 v37, v37, v59, -v68
	v_fma_f32 v103, v103, v39, -v68
	v_fma_f32 v11, v11, v10, -v68
	v_mul_f32_e32 v57, v69, v57
	v_mul_f32_e32 v37, v69, v37
	v_mul_f32_e32 v103, v69, v103
	v_mul_f32_e32 v11, v69, v11
	v_fma_mixlo_f16 v58, v57, v78, v94
	v_fma_mixlo_f16 v38, v37, v79, v95
	v_fma_mixlo_f16 v9, v103, v80, v96
	v_fma_mixlo_f16 v12, v11, v81, v97
	ds_write_b16 v65, v58 offset:2176
	ds_write_b16 v65, v38 offset:2448
	ds_write_b16 v65, v9 offset:2720
	ds_write_b16 v65, v12 offset:2992
	v_cvt_f32_f16_e32 v56, v26
	v_cvt_f32_f16_sdwa v59, v26 dst_sel:DWORD dst_unused:UNUSED_PAD src0_sel:WORD_1
	v_cvt_f32_f16_e32 v39, v27
	v_cvt_f32_f16_sdwa v10, v27 dst_sel:DWORD dst_unused:UNUSED_PAD src0_sel:WORD_1
	v_mul_f32_e32 v57, v56, v56
	v_mul_f32_e32 v37, v59, v59
	v_mul_f32_e32 v103, v39, v39
	v_mul_f32_e32 v11, v10, v10
	v_mul_f32_e32 v58, s41, v56
	v_mul_f32_e32 v38, s41, v59
	v_mul_f32_e32 v9, s41, v39
	v_mul_f32_e32 v12, s41, v10
	v_fma_f32 v57, v57, s40, 1.0
	v_fma_f32 v37, v37, s40, 1.0
	v_fma_f32 v103, v103, s40, 1.0
	v_fma_f32 v11, v11, s40, 1.0
	v_mul_f32_e32 v57, v57, v58
	v_mul_f32_e32 v37, v37, v38
	v_mul_f32_e32 v103, v103, v9
	v_mul_f32_e32 v11, v11, v12
	v_exp_f32_e32 v57, v57
	v_exp_f32_e32 v37, v37
	v_exp_f32_e32 v103, v103
	v_exp_f32_e32 v11, v11
	v_add_f32_e32 v57, 1.0, v57
	v_add_f32_e32 v37, 1.0, v37
	v_add_f32_e32 v103, 1.0, v103
	v_add_f32_e32 v11, 1.0, v11
	v_rcp_f32_e32 v57, v57
	v_rcp_f32_e32 v37, v37
	v_rcp_f32_e32 v103, v103
	v_rcp_f32_e32 v11, v11
	v_fma_f32 v57, v57, v56, -v68
	v_fma_f32 v37, v37, v59, -v68
	v_fma_f32 v103, v103, v39, -v68
	v_fma_f32 v11, v11, v10, -v68
	v_mul_f32_e32 v57, v69, v57
	v_mul_f32_e32 v37, v69, v37
	v_mul_f32_e32 v103, v69, v103
	v_mul_f32_e32 v11, v69, v11
	v_fma_mixlo_f16 v58, v57, v82, v98
	v_fma_mixlo_f16 v38, v37, v83, v99
	v_fma_mixlo_f16 v9, v103, v84, v100
	v_fma_mixlo_f16 v12, v11, v85, v101
	ds_write_b16 v65, v58 offset:3264
	ds_write_b16 v65, v38 offset:3536
	ds_write_b16 v65, v9 offset:3808
	ds_write_b16 v65, v12 offset:4080
	s_waitcnt lgkmcnt(0)
	s_barrier
	ds_read_b128 v[70:73], v66 offset:0
	ds_read_b128 v[74:77], v66 offset:4352
	ds_read_b128 v[78:81], v66 offset:8704
	ds_read_b128 v[82:85], v66 offset:13056
	ds_read_b128 v[86:89], v66 offset:64
	ds_read_b128 v[90:93], v66 offset:4416
	ds_read_b128 v[94:97], v66 offset:8768
	ds_read_b128 v[98:101], v66 offset:13120
	s_waitcnt vmcnt(11)
	s_waitcnt lgkmcnt(7)
	v_mfma_f32_16x16x32_f16 v[40:43], v[70:73], v[122:125], 0
	ds_read_b128 v[70:73], v66 offset:128
	s_waitcnt lgkmcnt(7)
	v_mfma_f32_16x16x32_f16 v[44:47], v[74:77], v[122:125], 0
	ds_read_b128 v[74:77], v66 offset:4480
	s_waitcnt lgkmcnt(7)
	v_mfma_f32_16x16x32_f16 v[48:51], v[78:81], v[122:125], 0
	ds_read_b128 v[78:81], v66 offset:8832
	s_waitcnt lgkmcnt(7)
	v_mfma_f32_16x16x32_f16 v[52:55], v[82:85], v[122:125], 0
	ds_read_b128 v[82:85], v66 offset:13184
	s_waitcnt lgkmcnt(7)
	v_mfma_f32_16x16x32_f16 v[40:43], v[86:89], v[126:129], v[40:43]
	ds_read_b128 v[86:89], v66 offset:192
	s_waitcnt lgkmcnt(7)
	v_mfma_f32_16x16x32_f16 v[44:47], v[90:93], v[126:129], v[44:47]
	ds_read_b128 v[90:93], v66 offset:4544
	s_waitcnt lgkmcnt(7)
	v_mfma_f32_16x16x32_f16 v[48:51], v[94:97], v[126:129], v[48:51]
	ds_read_b128 v[94:97], v66 offset:8896
	s_waitcnt lgkmcnt(7)
	v_mfma_f32_16x16x32_f16 v[52:55], v[98:101], v[126:129], v[52:55]
	ds_read_b128 v[98:101], v66 offset:13248
	s_waitcnt lgkmcnt(7)
	v_mfma_f32_16x16x32_f16 v[40:43], v[70:73], v[130:133], v[40:43]
	s_waitcnt lgkmcnt(6)
	v_mfma_f32_16x16x32_f16 v[44:47], v[74:77], v[130:133], v[44:47]
	s_waitcnt lgkmcnt(5)
	v_mfma_f32_16x16x32_f16 v[48:51], v[78:81], v[130:133], v[48:51]
	s_waitcnt lgkmcnt(4)
	v_mfma_f32_16x16x32_f16 v[52:55], v[82:85], v[130:133], v[52:55]
	s_waitcnt lgkmcnt(3)
	v_mfma_f32_16x16x32_f16 v[40:43], v[86:89], v[134:137], v[40:43]
	s_waitcnt lgkmcnt(2)
	v_mfma_f32_16x16x32_f16 v[44:47], v[90:93], v[134:137], v[44:47]
	s_waitcnt lgkmcnt(1)
	v_mfma_f32_16x16x32_f16 v[48:51], v[94:97], v[134:137], v[48:51]
	s_waitcnt lgkmcnt(0)
	v_mfma_f32_16x16x32_f16 v[52:55], v[98:101], v[134:137], v[52:55]
	s_add_u32 s62, s62, 0x8000
	s_addc_u32 s63, s63, 0
	s_cmp_eq_u32 s44, 0x380
	s_cbranch_scc1 .Lsgu_noaf
	global_load_dwordx4 v[122:125], v64, s[62:63] offset:0
	global_load_dwordx4 v[126:129], v64, s[62:63] offset:64
	global_load_dwordx4 v[130:133], v64, s[62:63] offset:128
	global_load_dwordx4 v[134:137], v64, s[62:63] offset:192
.Lsgu_noaf:
	s_nop 4
	v_cvt_f32_f16_e32 v56, v28
	v_cvt_f32_f16_sdwa v59, v28 dst_sel:DWORD dst_unused:UNUSED_PAD src0_sel:WORD_1
	v_cvt_f32_f16_e32 v39, v29
	v_cvt_f32_f16_sdwa v10, v29 dst_sel:DWORD dst_unused:UNUSED_PAD src0_sel:WORD_1
	v_mul_f32_e32 v57, v56, v56
	v_mul_f32_e32 v37, v59, v59
	v_mul_f32_e32 v103, v39, v39
	v_mul_f32_e32 v11, v10, v10
	v_mul_f32_e32 v58, s41, v56
	v_mul_f32_e32 v38, s41, v59
	v_mul_f32_e32 v9, s41, v39
	v_mul_f32_e32 v12, s41, v10
	v_fma_f32 v57, v57, s40, 1.0
	v_fma_f32 v37, v37, s40, 1.0
	v_fma_f32 v103, v103, s40, 1.0
	v_fma_f32 v11, v11, s40, 1.0
	v_mul_f32_e32 v57, v57, v58
	v_mul_f32_e32 v37, v37, v38
	v_mul_f32_e32 v103, v103, v9
	v_mul_f32_e32 v11, v11, v12
	v_exp_f32_e32 v57, v57
	v_exp_f32_e32 v37, v37
	v_exp_f32_e32 v103, v103
	v_exp_f32_e32 v11, v11
	v_add_f32_e32 v57, 1.0, v57
	v_add_f32_e32 v37, 1.0, v37
	v_add_f32_e32 v103, 1.0, v103
	v_add_f32_e32 v11, 1.0, v11
	v_rcp_f32_e32 v57, v57
	v_rcp_f32_e32 v37, v37
	v_rcp_f32_e32 v103, v103
	v_rcp_f32_e32 v11, v11
	v_mul_f32_e32 v57, v57, v56
	v_mul_f32_e32 v37, v37, v59
	v_mul_f32_e32 v103, v103, v39
	v_mul_f32_e32 v11, v11, v10
	v_add_f32_e32 v58, v40, v36
	v_add_f32_e32 v38, v41, v36
	v_add_f32_e32 v9, v42, v36
	v_add_f32_e32 v12, v43, v36
	v_mul_f32_e32 v57, v57, v58
	v_mul_f32_e32 v37, v37, v38
	v_mul_f32_e32 v103, v103, v9
	v_mul_f32_e32 v11, v11, v12
	v_cvt_pk_f16_f32 v14, v57, v37
	v_cvt_pk_f16_f32 v15, v103, v11
	global_store_dwordx2 v62, v[14:15], s[36:37] offset:0
	v_cvt_f32_f16_e32 v56, v30
	v_cvt_f32_f16_sdwa v59, v30 dst_sel:DWORD dst_unused:UNUSED_PAD src0_sel:WORD_1
	v_cvt_f32_f16_e32 v39, v31
	v_cvt_f32_f16_sdwa v10, v31 dst_sel:DWORD dst_unused:UNUSED_PAD src0_sel:WORD_1
	v_mul_f32_e32 v57, v56, v56
	v_mul_f32_e32 v37, v59, v59
	v_mul_f32_e32 v103, v39, v39
	v_mul_f32_e32 v11, v10, v10
	v_mul_f32_e32 v58, s41, v56
	v_mul_f32_e32 v38, s41, v59
	v_mul_f32_e32 v9, s41, v39
	v_mul_f32_e32 v12, s41, v10
	v_fma_f32 v57, v57, s40, 1.0
	v_fma_f32 v37, v37, s40, 1.0
	v_fma_f32 v103, v103, s40, 1.0
	v_fma_f32 v11, v11, s40, 1.0
	v_mul_f32_e32 v57, v57, v58
	v_mul_f32_e32 v37, v37, v38
	v_mul_f32_e32 v103, v103, v9
	v_mul_f32_e32 v11, v11, v12
	v_exp_f32_e32 v57, v57
	v_exp_f32_e32 v37, v37
	v_exp_f32_e32 v103, v103
	v_exp_f32_e32 v11, v11
	v_add_f32_e32 v57, 1.0, v57
	v_add_f32_e32 v37, 1.0, v37
	v_add_f32_e32 v103, 1.0, v103
	v_add_f32_e32 v11, 1.0, v11
	v_rcp_f32_e32 v57, v57
	v_rcp_f32_e32 v37, v37
	v_rcp_f32_e32 v103, v103
	v_rcp_f32_e32 v11, v11
	v_mul_f32_e32 v57, v57, v56
	v_mul_f32_e32 v37, v37, v59
	v_mul_f32_e32 v103, v103, v39
	v_mul_f32_e32 v11, v11, v10
	v_add_f32_e32 v58, v44, v36
	v_add_f32_e32 v38, v45, v36
	v_add_f32_e32 v9, v46, v36
	v_add_f32_e32 v12, v47, v36
	v_mul_f32_e32 v57, v57, v58
	v_mul_f32_e32 v37, v37, v38
	v_mul_f32_e32 v103, v103, v9
	v_mul_f32_e32 v11, v11, v12
	v_cvt_pk_f16_f32 v14, v57, v37
	v_cvt_pk_f16_f32 v15, v103, v11
	global_store_dwordx2 v62, v[14:15], s[36:37] offset:32
	v_cvt_f32_f16_e32 v56, v32
	v_cvt_f32_f16_sdwa v59, v32 dst_sel:DWORD dst_unused:UNUSED_PAD src0_sel:WORD_1
	v_cvt_f32_f16_e32 v39, v33
	v_cvt_f32_f16_sdwa v10, v33 dst_sel:DWORD dst_unused:UNUSED_PAD src0_sel:WORD_1
	v_mul_f32_e32 v57, v56, v56
	v_mul_f32_e32 v37, v59, v59
	v_mul_f32_e32 v103, v39, v39
	v_mul_f32_e32 v11, v10, v10
	v_mul_f32_e32 v58, s41, v56
	v_mul_f32_e32 v38, s41, v59
	v_mul_f32_e32 v9, s41, v39
	v_mul_f32_e32 v12, s41, v10
	v_fma_f32 v57, v57, s40, 1.0
	v_fma_f32 v37, v37, s40, 1.0
	v_fma_f32 v103, v103, s40, 1.0
	v_fma_f32 v11, v11, s40, 1.0
	v_mul_f32_e32 v57, v57, v58
	v_mul_f32_e32 v37, v37, v38
	v_mul_f32_e32 v103, v103, v9
	v_mul_f32_e32 v11, v11, v12
	v_exp_f32_e32 v57, v57
	v_exp_f32_e32 v37, v37
	v_exp_f32_e32 v103, v103
	v_exp_f32_e32 v11, v11
	v_add_f32_e32 v57, 1.0, v57
	v_add_f32_e32 v37, 1.0, v37
	v_add_f32_e32 v103, 1.0, v103
	v_add_f32_e32 v11, 1.0, v11
	v_rcp_f32_e32 v57, v57
	v_rcp_f32_e32 v37, v37
	v_rcp_f32_e32 v103, v103
	v_rcp_f32_e32 v11, v11
	v_mul_f32_e32 v57, v57, v56
	v_mul_f32_e32 v37, v37, v59
	v_mul_f32_e32 v103, v103, v39
	v_mul_f32_e32 v11, v11, v10
	v_add_f32_e32 v58, v48, v36
	v_add_f32_e32 v38, v49, v36
	v_add_f32_e32 v9, v50, v36
	v_add_f32_e32 v12, v51, v36
	v_mul_f32_e32 v57, v57, v58
	v_mul_f32_e32 v37, v37, v38
	v_mul_f32_e32 v103, v103, v9
	v_mul_f32_e32 v11, v11, v12
	v_cvt_pk_f16_f32 v14, v57, v37
	v_cvt_pk_f16_f32 v15, v103, v11
	global_store_dwordx2 v62, v[14:15], s[36:37] offset:64
	v_cvt_f32_f16_e32 v56, v34
	v_cvt_f32_f16_sdwa v59, v34 dst_sel:DWORD dst_unused:UNUSED_PAD src0_sel:WORD_1
	v_cvt_f32_f16_e32 v39, v35
	v_cvt_f32_f16_sdwa v10, v35 dst_sel:DWORD dst_unused:UNUSED_PAD src0_sel:WORD_1
	v_mul_f32_e32 v57, v56, v56
	v_mul_f32_e32 v37, v59, v59
	v_mul_f32_e32 v103, v39, v39
	v_mul_f32_e32 v11, v10, v10
	v_mul_f32_e32 v58, s41, v56
	v_mul_f32_e32 v38, s41, v59
	v_mul_f32_e32 v9, s41, v39
	v_mul_f32_e32 v12, s41, v10
	v_fma_f32 v57, v57, s40, 1.0
	v_fma_f32 v37, v37, s40, 1.0
	v_fma_f32 v103, v103, s40, 1.0
	v_fma_f32 v11, v11, s40, 1.0
	v_mul_f32_e32 v57, v57, v58
	v_mul_f32_e32 v37, v37, v38
	v_mul_f32_e32 v103, v103, v9
	v_mul_f32_e32 v11, v11, v12
	v_exp_f32_e32 v57, v57
	v_exp_f32_e32 v37, v37
	v_exp_f32_e32 v103, v103
	v_exp_f32_e32 v11, v11
	v_add_f32_e32 v57, 1.0, v57
	v_add_f32_e32 v37, 1.0, v37
	v_add_f32_e32 v103, 1.0, v103
	v_add_f32_e32 v11, 1.0, v11
	v_rcp_f32_e32 v57, v57
	v_rcp_f32_e32 v37, v37
	v_rcp_f32_e32 v103, v103
	v_rcp_f32_e32 v11, v11
	v_mul_f32_e32 v57, v57, v56
	v_mul_f32_e32 v37, v37, v59
	v_mul_f32_e32 v103, v103, v39
	v_mul_f32_e32 v11, v11, v10
	v_add_f32_e32 v58, v52, v36
	v_add_f32_e32 v38, v53, v36
	v_add_f32_e32 v9, v54, v36
	v_add_f32_e32 v12, v55, v36
	v_mul_f32_e32 v57, v57, v58
	v_mul_f32_e32 v37, v37, v38
	v_mul_f32_e32 v103, v103, v9
	v_mul_f32_e32 v11, v11, v12
	v_cvt_pk_f16_f32 v14, v57, v37
	v_cvt_pk_f16_f32 v15, v103, v11
	global_store_dwordx2 v62, v[14:15], s[36:37] offset:96
	v_add_u32_e32 v62, 0x80, v62
	v_xor_b32_e32 v65, 0x8000, v65
	v_xor_b32_e32 v66, 0x8000, v66
	s_addk_i32 s44, 0x80
	s_waitcnt vmcnt(8)
	s_cmpk_lg_i32 s44, 0x400
	s_cbranch_scc1 .Lsgu_g8
	s_barrier
	v_readlane_b32 s0, v253, 38
	s_add_i32 s25, s25, s54
	s_add_i32 s24, s24, s0
	s_add_i32 s7, s7, s0
	s_cmp_lt_i32 s25, s6
	s_cbranch_scc1 .LBB0_74

.LBB0_185:
	ds_read_b128 v[34:37], v217 offset:21120
	ds_read_b128 v[38:41], v217 offset:21760
	ds_read_b128 v[42:45], v217 offset:22400
	ds_read_b128 v[66:69], v217 offset:26240
	ds_read_b128 v[70:73], v217 offset:26880
	ds_read_b128 v[74:77], v217 offset:27520
	s_waitcnt lgkmcnt(3)
	v_fma_mix_f32 v238, v38, v84, 0 op_sel:[0,0,0] op_sel_hi:[1,0,0]
	v_fma_mix_f32 v239, v38, v85, 0 op_sel:[1,0,0] op_sel_hi:[1,0,0]
	v_fma_mix_f32 v240, v39, v90, 0 op_sel:[0,0,0] op_sel_hi:[1,0,0]
	v_fma_mix_f32 v241, v39, v91, 0 op_sel:[1,0,0] op_sel_hi:[1,0,0]
	v_fma_mix_f32 v242, v40, v96, 0 op_sel:[0,0,0] op_sel_hi:[1,0,0]
	v_fma_mix_f32 v243, v40, v97, 0 op_sel:[1,0,0] op_sel_hi:[1,0,0]
	v_fma_mix_f32 v244, v41, v102, 0 op_sel:[0,0,0] op_sel_hi:[1,0,0]
	v_fma_mix_f32 v245, v41, v103, 0 op_sel:[1,0,0] op_sel_hi:[1,0,0]
	v_fma_mix_f32 v238, v34, v82, v238 op_sel:[0,0,0] op_sel_hi:[1,0,0]
	v_fma_mix_f32 v239, v34, v83, v239 op_sel:[1,0,0] op_sel_hi:[1,0,0]
	v_fma_mix_f32 v240, v35, v88, v240 op_sel:[0,0,0] op_sel_hi:[1,0,0]
	v_fma_mix_f32 v241, v35, v89, v241 op_sel:[1,0,0] op_sel_hi:[1,0,0]
	v_fma_mix_f32 v242, v36, v94, v242 op_sel:[0,0,0] op_sel_hi:[1,0,0]
	v_fma_mix_f32 v243, v36, v95, v243 op_sel:[1,0,0] op_sel_hi:[1,0,0]
	v_fma_mix_f32 v244, v37, v100, v244 op_sel:[0,0,0] op_sel_hi:[1,0,0]
	v_fma_mix_f32 v245, v37, v101, v245 op_sel:[1,0,0] op_sel_hi:[1,0,0]
	v_fma_mix_f32 v238, v42, v86, v238 op_sel:[0,0,0] op_sel_hi:[1,0,0]
	v_fma_mix_f32 v239, v42, v87, v239 op_sel:[1,0,0] op_sel_hi:[1,0,0]
	v_fma_mix_f32 v240, v43, v92, v240 op_sel:[0,0,0] op_sel_hi:[1,0,0]
	v_fma_mix_f32 v241, v43, v93, v241 op_sel:[1,0,0] op_sel_hi:[1,0,0]
	v_fma_mix_f32 v242, v44, v98, v242 op_sel:[0,0,0] op_sel_hi:[1,0,0]
	v_fma_mix_f32 v243, v44, v99, v243 op_sel:[1,0,0] op_sel_hi:[1,0,0]
	v_fma_mix_f32 v244, v45, v104, v244 op_sel:[0,0,0] op_sel_hi:[1,0,0]
	v_fma_mix_f32 v245, v45, v105, v245 op_sel:[1,0,0] op_sel_hi:[1,0,0]
	s_waitcnt lgkmcnt(0)
	v_fma_mix_f32 v246, v70, v84, 0 op_sel:[0,0,0] op_sel_hi:[1,0,0]
	v_fma_mix_f32 v247, v70, v85, 0 op_sel:[1,0,0] op_sel_hi:[1,0,0]
	v_fma_mix_f32 v248, v71, v90, 0 op_sel:[0,0,0] op_sel_hi:[1,0,0]
	v_fma_mix_f32 v249, v71, v91, 0 op_sel:[1,0,0] op_sel_hi:[1,0,0]
	v_fma_mix_f32 v58, v72, v96, 0 op_sel:[0,0,0] op_sel_hi:[1,0,0]
	v_fma_mix_f32 v59, v72, v97, 0 op_sel:[1,0,0] op_sel_hi:[1,0,0]
	v_fma_mix_f32 v60, v73, v102, 0 op_sel:[0,0,0] op_sel_hi:[1,0,0]
	v_fma_mix_f32 v61, v73, v103, 0 op_sel:[1,0,0] op_sel_hi:[1,0,0]
	v_fma_mix_f32 v246, v66, v82, v246 op_sel:[0,0,0] op_sel_hi:[1,0,0]
	v_fma_mix_f32 v247, v66, v83, v247 op_sel:[1,0,0] op_sel_hi:[1,0,0]
	v_fma_mix_f32 v248, v67, v88, v248 op_sel:[0,0,0] op_sel_hi:[1,0,0]
	v_fma_mix_f32 v249, v67, v89, v249 op_sel:[1,0,0] op_sel_hi:[1,0,0]
	v_fma_mix_f32 v58, v68, v94, v58 op_sel:[0,0,0] op_sel_hi:[1,0,0]
	v_fma_mix_f32 v59, v68, v95, v59 op_sel:[1,0,0] op_sel_hi:[1,0,0]
	v_fma_mix_f32 v60, v69, v100, v60 op_sel:[0,0,0] op_sel_hi:[1,0,0]
	v_fma_mix_f32 v61, v69, v101, v61 op_sel:[1,0,0] op_sel_hi:[1,0,0]
	v_fma_mix_f32 v246, v74, v86, v246 op_sel:[0,0,0] op_sel_hi:[1,0,0]
	v_fma_mix_f32 v247, v74, v87, v247 op_sel:[1,0,0] op_sel_hi:[1,0,0]
	v_fma_mix_f32 v248, v75, v92, v248 op_sel:[0,0,0] op_sel_hi:[1,0,0]
	v_fma_mix_f32 v249, v75, v93, v249 op_sel:[1,0,0] op_sel_hi:[1,0,0]
	v_fma_mix_f32 v58, v76, v98, v58 op_sel:[0,0,0] op_sel_hi:[1,0,0]
	v_fma_mix_f32 v59, v76, v99, v59 op_sel:[1,0,0] op_sel_hi:[1,0,0]
	v_fma_mix_f32 v60, v77, v104, v60 op_sel:[0,0,0] op_sel_hi:[1,0,0]
	v_fma_mix_f32 v61, v77, v105, v61 op_sel:[1,0,0] op_sel_hi:[1,0,0]
	s_cmp_eq_u32 s45, 3
	s_cbranch_scc1 .Ls1_w3
	v_add_u32_e32 v3, v157, v173
	ds_write_b128 v3, v[238:241]
	ds_write_b128 v3, v[242:245] offset:16
	ds_write_b128 v211, v[246:249]
	ds_write_b128 v211, v[58:61] offset:16
	s_cmp_lg_u32 s45, 1
	s_cbranch_scc1 .Ls1_alora
	v_mul_f32_e32 v4, v239, v175
	v_mul_f32_e32 v34, v238, v174
	v_mul_f32_e32 v4, v4, v4
	v_fmac_f32_e32 v4, v34, v34
	v_mul_f32_e32 v34, v240, v176
	v_fmac_f32_e32 v4, v34, v34
	v_mul_f32_e32 v34, v241, v177
	v_fmac_f32_e32 v4, v34, v34
	v_mul_f32_e32 v34, v242, v178
	v_fmac_f32_e32 v4, v34, v34
	v_mul_f32_e32 v34, v243, v179
	v_fmac_f32_e32 v4, v34, v34
	v_mul_f32_e32 v34, v244, v180
	v_fmac_f32_e32 v4, v34, v34
	v_mul_f32_e32 v34, v245, v181
	v_fmac_f32_e32 v4, v34, v34
	v_mul_f32_e32 v5, v247, v175
	v_mul_f32_e32 v35, v246, v174
	v_mul_f32_e32 v5, v5, v5
	v_fmac_f32_e32 v5, v35, v35
	v_mul_f32_e32 v35, v248, v176
	v_fmac_f32_e32 v5, v35, v35
	v_mul_f32_e32 v35, v249, v177
	v_fmac_f32_e32 v5, v35, v35
	v_mul_f32_e32 v35, v58, v178
	v_fmac_f32_e32 v5, v35, v35
	v_mul_f32_e32 v35, v59, v179
	v_fmac_f32_e32 v5, v35, v35
	v_mul_f32_e32 v35, v60, v180
	v_fmac_f32_e32 v5, v35, v35
	v_mul_f32_e32 v35, v61, v181
	v_fmac_f32_e32 v5, v35, v35
	s_nop 1
	v_add_f32_dpp v4, v4, v4 quad_perm:[1,0,3,2] row_mask:0xf bank_mask:0xf
	v_add_f32_dpp v5, v5, v5 quad_perm:[1,0,3,2] row_mask:0xf bank_mask:0xf
	s_nop 1
	v_add_f32_dpp v4, v4, v4 quad_perm:[2,3,0,1] row_mask:0xf bank_mask:0xf
	v_add_f32_dpp v5, v5, v5 quad_perm:[2,3,0,1] row_mask:0xf bank_mask:0xf
	s_nop 1
	v_add_f32_dpp v4, v4, v4 row_half_mirror row_mask:0xf bank_mask:0xf
	v_add_f32_dpp v5, v5, v5 row_half_mirror row_mask:0xf bank_mask:0xf
	s_and_saveexec_b64 s[48:49], s[14:15]
	v_max_f32_e32 v4, 0x179abe15, v4
	v_max_f32_e32 v5, 0x179abe15, v5
	v_rsq_f32_e32 v4, v4
	v_rsq_f32_e32 v5, v5
	s_nop 0
	ds_write_b32 v182, v4 offset:20992
	ds_write_b32 v182, v5 offset:21024
	s_or_b64 exec, exec, s[48:49]
	s_branch .Ls1_alora
.Ls1_w3:
	s_mov_b32 s48, 0x4038aa3b
	v_mul_f32_e32 v238, s48, v238
	v_mul_f32_e32 v239, s48, v239
	v_mul_f32_e32 v240, s48, v240
	v_mul_f32_e32 v241, s48, v241
	v_mul_f32_e32 v242, s48, v242
	v_mul_f32_e32 v243, s48, v243
	v_mul_f32_e32 v244, s48, v244
	v_mul_f32_e32 v245, s48, v245
	v_exp_f32_e32 v238, v238
	v_exp_f32_e32 v239, v239
	v_exp_f32_e32 v240, v240
	v_exp_f32_e32 v241, v241
	v_exp_f32_e32 v242, v242
	v_exp_f32_e32 v243, v243
	v_exp_f32_e32 v244, v244
	v_exp_f32_e32 v245, v245
	v_add_f32_e32 v238, 1.0, v238
	v_add_f32_e32 v239, 1.0, v239
	v_add_f32_e32 v240, 1.0, v240
	v_add_f32_e32 v241, 1.0, v241
	v_add_f32_e32 v242, 1.0, v242
	v_add_f32_e32 v243, 1.0, v243
	v_add_f32_e32 v244, 1.0, v244
	v_add_f32_e32 v245, 1.0, v245
	v_rcp_f32_e32 v238, v238
	v_rcp_f32_e32 v239, v239
	v_rcp_f32_e32 v240, v240
	v_rcp_f32_e32 v241, v241
	v_rcp_f32_e32 v242, v242
	v_rcp_f32_e32 v243, v243
	v_rcp_f32_e32 v244, v244
	v_rcp_f32_e32 v245, v245
	v_mul_f32_e32 v246, s48, v246
	v_mul_f32_e32 v247, s48, v247
	v_mul_f32_e32 v248, s48, v248
	v_mul_f32_e32 v249, s48, v249
	v_mul_f32_e32 v58, s48, v58
	v_mul_f32_e32 v59, s48, v59
	v_mul_f32_e32 v60, s48, v60
	v_mul_f32_e32 v61, s48, v61
	v_exp_f32_e32 v246, v246
	v_exp_f32_e32 v247, v247
	v_exp_f32_e32 v248, v248
	v_exp_f32_e32 v249, v249
	v_exp_f32_e32 v58, v58
	v_exp_f32_e32 v59, v59
	v_exp_f32_e32 v60, v60
	v_exp_f32_e32 v61, v61
	v_add_f32_e32 v246, 1.0, v246
	v_add_f32_e32 v247, 1.0, v247
	v_add_f32_e32 v248, 1.0, v248
	v_add_f32_e32 v249, 1.0, v249
	v_add_f32_e32 v58, 1.0, v58
	v_add_f32_e32 v59, 1.0, v59
	v_add_f32_e32 v60, 1.0, v60
	v_add_f32_e32 v61, 1.0, v61
	v_rcp_f32_e32 v246, v246
	v_rcp_f32_e32 v247, v247
	v_rcp_f32_e32 v248, v248
	v_rcp_f32_e32 v249, v249
	v_rcp_f32_e32 v58, v58
	v_rcp_f32_e32 v59, v59
	v_rcp_f32_e32 v60, v60
	v_rcp_f32_e32 v61, v61
	v_pk_fma_f32 v[238:239], v[238:239], 2.0, 1.0 op_sel_hi:[1,0,0] neg_lo:[1,0,0] neg_hi:[1,0,0]
	v_pk_fma_f32 v[240:241], v[240:241], 2.0, 1.0 op_sel_hi:[1,0,0] neg_lo:[1,0,0] neg_hi:[1,0,0]
	v_pk_fma_f32 v[242:243], v[242:243], 2.0, 1.0 op_sel_hi:[1,0,0] neg_lo:[1,0,0] neg_hi:[1,0,0]
	v_pk_fma_f32 v[244:245], v[244:245], 2.0, 1.0 op_sel_hi:[1,0,0] neg_lo:[1,0,0] neg_hi:[1,0,0]
	s_nop 0
	v_cvt_pk_f16_f32 v34, v238, v239
	v_cvt_pk_f16_f32 v35, v240, v241
	v_cvt_pk_f16_f32 v36, v242, v243
	v_cvt_pk_f16_f32 v37, v244, v245
	v_pk_fma_f32 v[246:247], v[246:247], 2.0, 1.0 op_sel_hi:[1,0,0] neg_lo:[1,0,0] neg_hi:[1,0,0]
	v_pk_fma_f32 v[248:249], v[248:249], 2.0, 1.0 op_sel_hi:[1,0,0] neg_lo:[1,0,0] neg_hi:[1,0,0]
	v_pk_fma_f32 v[58:59], v[58:59], 2.0, 1.0 op_sel_hi:[1,0,0] neg_lo:[1,0,0] neg_hi:[1,0,0]
	v_pk_fma_f32 v[60:61], v[60:61], 2.0, 1.0 op_sel_hi:[1,0,0] neg_lo:[1,0,0] neg_hi:[1,0,0]
	s_nop 0
	v_cvt_pk_f16_f32 v38, v246, v247
	v_cvt_pk_f16_f32 v39, v248, v249
	v_cvt_pk_f16_f32 v40, v58, v59
	v_cvt_pk_f16_f32 v41, v60, v61
	v_add_u32_e32 v3, v156, v183
	ds_write_b128 v3, v[34:37] offset:16384
	ds_write_b128 v3, v[38:41] offset:17536
.Ls1_alora:
	s_and_saveexec_b64 s[88:89], s[16:17]
	s_cbranch_execz .LBB0_201
	ds_read_b128 v[66:69], v212 offset:21632
	ds_read_b128 v[70:73], v212 offset:22272
	ds_read_b128 v[74:77], v212 offset:22912
	s_waitcnt lgkmcnt(0)
	v_fma_mix_f32 v238, v70, v108, 0 op_sel:[0,0,0] op_sel_hi:[1,0,0]
	v_fma_mix_f32 v239, v70, v109, 0 op_sel:[1,0,0] op_sel_hi:[1,0,0]
	v_fma_mix_f32 v240, v71, v114, 0 op_sel:[0,0,0] op_sel_hi:[1,0,0]
	v_fma_mix_f32 v241, v71, v115, 0 op_sel:[1,0,0] op_sel_hi:[1,0,0]
	v_fma_mix_f32 v242, v72, v120, 0 op_sel:[0,0,0] op_sel_hi:[1,0,0]
	v_fma_mix_f32 v243, v72, v121, 0 op_sel:[1,0,0] op_sel_hi:[1,0,0]
	v_fma_mix_f32 v244, v73, v126, 0 op_sel:[0,0,0] op_sel_hi:[1,0,0]
	v_fma_mix_f32 v245, v73, v127, 0 op_sel:[1,0,0] op_sel_hi:[1,0,0]
	v_fma_mix_f32 v238, v66, v106, v238 op_sel:[0,0,0] op_sel_hi:[1,0,0]
	v_fma_mix_f32 v239, v66, v107, v239 op_sel:[1,0,0] op_sel_hi:[1,0,0]
	v_fma_mix_f32 v240, v67, v112, v240 op_sel:[0,0,0] op_sel_hi:[1,0,0]
	v_fma_mix_f32 v241, v67, v113, v241 op_sel:[1,0,0] op_sel_hi:[1,0,0]
	v_fma_mix_f32 v242, v68, v118, v242 op_sel:[0,0,0] op_sel_hi:[1,0,0]
	v_fma_mix_f32 v243, v68, v119, v243 op_sel:[1,0,0] op_sel_hi:[1,0,0]
	v_fma_mix_f32 v244, v69, v124, v244 op_sel:[0,0,0] op_sel_hi:[1,0,0]
	v_fma_mix_f32 v245, v69, v125, v245 op_sel:[1,0,0] op_sel_hi:[1,0,0]
	v_fma_mix_f32 v238, v74, v110, v238 op_sel:[0,0,0] op_sel_hi:[1,0,0]
	v_fma_mix_f32 v239, v74, v111, v239 op_sel:[1,0,0] op_sel_hi:[1,0,0]
	v_fma_mix_f32 v240, v75, v116, v240 op_sel:[0,0,0] op_sel_hi:[1,0,0]
	v_fma_mix_f32 v241, v75, v117, v241 op_sel:[1,0,0] op_sel_hi:[1,0,0]
	v_fma_mix_f32 v242, v76, v122, v242 op_sel:[0,0,0] op_sel_hi:[1,0,0]
	v_fma_mix_f32 v243, v76, v123, v243 op_sel:[1,0,0] op_sel_hi:[1,0,0]
	v_fma_mix_f32 v244, v77, v128, v244 op_sel:[0,0,0] op_sel_hi:[1,0,0]
	v_fma_mix_f32 v245, v77, v129, v245 op_sel:[1,0,0] op_sel_hi:[1,0,0]
	v_cvt_pk_f16_f32 v34, v238, v239
	v_cvt_pk_f16_f32 v35, v240, v241
	v_cvt_pk_f16_f32 v36, v242, v243
	v_cvt_pk_f16_f32 v37, v244, v245
	ds_write_b128 v213, v[34:37] offset:18688

.LBB0_231:
	s_or_b64 exec, exec, s[48:49]
	ds_read_b128 v[34:37], v161 offset:51072
	ds_read_b128 v[38:41], v161 offset:51136
	ds_read_b128 v[58:61], v161 offset:51200
	v_add_u32_e32 v3, 0x7800, v215
	v_add_u32_e32 v4, 0x9800, v215
	s_waitcnt lgkmcnt(2)
	v_pk_mul_f32 v[48:49], v[48:49], v[36:37]
	s_waitcnt lgkmcnt(1)
	v_pk_mul_f32 v[44:45], v[64:65], v[40:41]
	v_pk_mul_f32 v[42:43], v[56:57], v[38:39]
	ds_read2_b64 v[38:41], v3 offset0:240 offset1:244
	v_pk_mul_f32 v[46:47], v[46:47], v[34:35]
	s_waitcnt lgkmcnt(1)
	v_pk_mul_f32 v[36:37], v[62:63], v[60:61]
	v_pk_mul_f32 v[34:35], v[54:55], v[58:59]
	ds_read2_b64 v[58:61], v4 offset0:80 offset1:84
	ds_read_b128 v[54:57], v161 offset:51264
	ds_read2_b64 v[70:73], v3 offset0:248 offset1:252
	v_cvt_pk_f16_f32 v65, v44, v45
	v_cvt_pk_f16_f32 v63, v48, v49
	v_cvt_pk_f16_f32 v64, v42, v43
	v_cvt_pk_f16_f32 v62, v46, v47
	ds_read_b128 v[74:77], v163
	s_cmp_lt_i32 s45, 2
	s_waitcnt lgkmcnt(4)
	v_mfma_f32_16x16x32_f16 v[66:69], v[38:41], v[62:65], 0
	s_waitcnt lgkmcnt(2)
	v_pk_mul_f32 v[40:41], v[52:53], v[56:57]
	v_pk_mul_f32 v[38:39], v[50:51], v[54:55]
	ds_read_b128 v[50:53], v162
	v_mfma_f32_16x16x32_f16 v[54:57], v[58:61], v[62:65], 0
	v_cvt_pk_f16_f32 v65, v40, v41
	v_cvt_pk_f16_f32 v63, v36, v37
	v_cvt_pk_f16_f32 v64, v38, v39
	v_cvt_pk_f16_f32 v62, v34, v35
	s_waitcnt lgkmcnt(2)
	s_nop 0
	v_mfma_f32_16x16x32_f16 v[58:61], v[70:73], v[62:65], v[66:69]
	ds_read_b128 v[70:73], v163 offset:64
	s_nop 1
	ds_read_b128 v[66:69], v162 offset:64
	s_waitcnt lgkmcnt(2)
	v_mfma_f32_16x16x32_f16 v[50:53], v[50:53], v[74:77], 0
	s_waitcnt lgkmcnt(0)
	v_mfma_f32_16x16x32_f16 v[50:53], v[66:69], v[70:73], v[50:53]
	ds_read2_b64 v[66:69], v4 offset0:88 offset1:92
	s_waitcnt lgkmcnt(0)
	v_mfma_f32_16x16x32_f16 v[54:57], v[66:69], v[62:65], v[54:57]
	s_cbranch_scc1 .LBB0_235
	s_cmp_eq_u32 s45, 2
	s_cselect_b64 s[88:89], -1, 0
	s_cbranch_execz .LBB0_236
	s_branch .LBB0_237
.LBB0_235:
	s_mov_b64 s[88:89], 0
